# v4: plus KMEAN block-mean loop with 32 loads in flight (was one load per wait), diff-attention epilogue gain loads pipelined 8 deep with counted waits
# speedup vs baseline: 1.0072x; 1.0072x over previous
; __device__ __forceinline__ float bflo(unsigned w) { return __uint_as_float(w << 16); }
; __device__ __forceinline__ float bfhi(unsigned w) { return __uint_as_float(w & 0xffff0000u); }
; __device__ __forceinline__ float half_sum(float v) { float a, b; half_pair(v, a, b); return a + b; }
; __global__ void __launch_bounds__(NWAVES * 64, 2) mega_fwd(Args args) {
;     ...
;                     const float inv = 1.0f / half_sum(l_);
;                     bf16* srow = STASH + (size_t)(tokb + qw + r32) * 1024 + h * 128;
;                     if (mp == 0) stash_o(o, inv, srow, hi);
;                     else {
;                         float ss = 0.f;
; #pragma unroll
;                         for (int db = 0; db < 4; ++db)
; #pragma unroll
;                             for (int ig = 0; ig < 4; ++ig) { const v2u o1w = *(const v2u*)(srow + db * 32 + ig * 8 + 4 * hi); const f32x4 o1 = {bflo(o1w.x), bfhi(o1w.x), bflo(o1w.y), bfhi(o1w.y)};
; #pragma unroll
;                                 for (int e = 0; e < 4; ++e) { const float a = o1[e] - lam * (o[db][4 * ig + e] * inv); o[db][4 * ig + e] = a; ss += a * a; } }
.LBB0_285:
	v_mov_b32_e32 v0, v80
	s_nop 1
	v_permlane32_swap_b32_e32 v80, v0
	v_add_f32_e32 v0, v80, v0
	v_div_scale_f32 v2, s[40:41], v0, v0, 1.0
	v_rcp_f32_e32 v3, v2
	s_mov_b64 s[92:93], -1
	v_fma_f32 v4, -v2, v3, 1.0
	v_fmac_f32_e32 v3, v4, v3
	v_div_scale_f32 v4, vcc, 1.0, v0, 1.0
	v_mul_f32_e32 v5, v4, v3
	v_fma_f32 v6, -v2, v5, v4
	v_fmac_f32_e32 v5, v6, v3
	v_fma_f32 v2, -v2, v5, v4
	v_div_fmas_f32 v2, v2, v3, v5
	v_div_fixup_f32 v0, v2, v0, 1.0
	s_andn2_b64 vcc, exec, s[90:91]
	s_cbranch_vccnz .LBB0_287
	global_load_dwordx2 v[10:11], v[232:233], off
	global_load_dwordx2 v[82:83], v[232:233], off offset:16
	global_load_dwordx2 v[92:93], v[232:233], off offset:32
	global_load_dwordx2 v[100:101], v[232:233], off offset:48
	global_load_dwordx2 v[108:109], v[232:233], off offset:64
	global_load_dwordx2 v[112:113], v[232:233], off offset:80
	global_load_dwordx2 v[106:107], v[232:233], off offset:96
	global_load_dwordx2 v[102:103], v[232:233], off offset:112
	global_load_dwordx2 v[98:99], v[232:233], off offset:128
	global_load_dwordx2 v[94:95], v[232:233], off offset:144
	global_load_dwordx2 v[90:91], v[232:233], off offset:160
	global_load_dwordx2 v[86:87], v[232:233], off offset:176
	global_load_dwordx2 v[84:85], v[232:233], off offset:192
	global_load_dwordx2 v[80:81], v[232:233], off offset:208
	global_load_dwordx2 v[12:13], v[232:233], off offset:224
	global_load_dwordx2 v[8:9], v[232:233], off offset:240
	v_pk_mul_f32 v[14:15], v[0:1], v[66:67] op_sel_hi:[0,1]
	v_pk_mul_f32 v[96:97], v[0:1], v[70:71] op_sel_hi:[0,1]
	v_pk_mul_f32 v[104:105], v[0:1], v[74:75] op_sel_hi:[0,1]
	v_pk_mul_f32 v[110:111], v[0:1], v[78:79] op_sel_hi:[0,1]
	s_waitcnt vmcnt(21)
	v_pk_mul_f32 v[114:115], v[0:1], v[50:51] op_sel_hi:[0,1]
	s_load_dwordx2 s[92:93], s[0:1], 0x40
	s_waitcnt vmcnt(19)
	v_lshlrev_b32_e32 v121, 2, v172
	v_pk_mul_f32 v[116:117], v[0:1], v[54:55] op_sel_hi:[0,1]
	v_pk_mul_f32 v[118:119], v[0:1], v[58:59] op_sel_hi:[0,1]
	v_pk_mul_f32 v[138:139], v[0:1], v[30:31] op_sel_hi:[0,1]
	s_waitcnt lgkmcnt(0)
	global_load_dwordx4 v[2:5], v121, s[92:93]
	s_mov_b32 s40, 0x800000
	s_waitcnt vmcnt(16)
	v_lshlrev_b32_e32 v6, 16, v11
	v_and_b32_e32 v7, 0xffff0000, v11
	v_pk_fma_f32 v[6:7], v[174:175], v[14:15], v[6:7] neg_lo:[1,0,0] neg_hi:[1,0,0]
	v_lshlrev_b32_e32 v14, 16, v10
	v_and_b32_e32 v15, 0xffff0000, v10
	v_pk_mul_f32 v[10:11], v[0:1], v[64:65] op_sel_hi:[0,1]
	v_pk_fma_f32 v[10:11], v[174:175], v[10:11], v[14:15] neg_lo:[1,0,0] neg_hi:[1,0,0]
	v_mul_f32_e32 v88, v7, v7
	v_mul_f32_e32 v14, v11, v11
	v_pk_fma_f32 v[14:15], v[10:11], v[10:11], v[14:15] op_sel_hi:[1,1,0]
	s_nop 0
	v_pk_fma_f32 v[14:15], v[6:7], v[6:7], v[14:15]
	s_nop 0
	v_pk_add_f32 v[88:89], v[14:15], v[88:89] op_sel_hi:[1,0]
	s_waitcnt vmcnt(15)
	v_lshlrev_b32_e32 v14, 16, v83
	v_and_b32_e32 v15, 0xffff0000, v83
	v_pk_fma_f32 v[14:15], v[174:175], v[96:97], v[14:15] neg_lo:[1,0,0] neg_hi:[1,0,0]
	v_lshlrev_b32_e32 v96, 16, v82
	v_and_b32_e32 v97, 0xffff0000, v82
	v_pk_mul_f32 v[82:83], v[0:1], v[68:69] op_sel_hi:[0,1]
	v_pk_fma_f32 v[82:83], v[174:175], v[82:83], v[96:97] neg_lo:[1,0,0] neg_hi:[1,0,0]
	s_nop 0
	v_pk_fma_f32 v[88:89], v[82:83], v[82:83], v[88:89]
	v_mul_f32_e32 v96, v83, v83
	v_pk_add_f32 v[88:89], v[88:89], v[96:97] op_sel_hi:[1,0]
	v_mul_f32_e32 v96, v15, v15
	v_pk_fma_f32 v[88:89], v[14:15], v[14:15], v[88:89]
	s_nop 0
	v_pk_add_f32 v[96:97], v[88:89], v[96:97] op_sel_hi:[1,0]
	s_waitcnt vmcnt(14)
	v_lshlrev_b32_e32 v88, 16, v93
	v_and_b32_e32 v89, 0xffff0000, v93
	v_pk_fma_f32 v[88:89], v[174:175], v[104:105], v[88:89] neg_lo:[1,0,0] neg_hi:[1,0,0]
	v_lshlrev_b32_e32 v104, 16, v92
	v_and_b32_e32 v105, 0xffff0000, v92
	v_pk_mul_f32 v[92:93], v[0:1], v[72:73] op_sel_hi:[0,1]
	v_pk_fma_f32 v[92:93], v[174:175], v[92:93], v[104:105] neg_lo:[1,0,0] neg_hi:[1,0,0]
	s_nop 0
	v_pk_fma_f32 v[96:97], v[92:93], v[92:93], v[96:97]
	v_mul_f32_e32 v104, v93, v93
	v_pk_add_f32 v[96:97], v[96:97], v[104:105] op_sel_hi:[1,0]
	v_mul_f32_e32 v104, v89, v89
	v_pk_fma_f32 v[96:97], v[88:89], v[88:89], v[96:97]
	s_nop 0
	v_pk_add_f32 v[104:105], v[96:97], v[104:105] op_sel_hi:[1,0]
	s_waitcnt vmcnt(13)
	v_lshlrev_b32_e32 v96, 16, v101
	v_and_b32_e32 v97, 0xffff0000, v101
	v_pk_fma_f32 v[96:97], v[174:175], v[110:111], v[96:97] neg_lo:[1,0,0] neg_hi:[1,0,0]
	v_lshlrev_b32_e32 v110, 16, v100
	v_and_b32_e32 v111, 0xffff0000, v100
	v_pk_mul_f32 v[100:101], v[0:1], v[76:77] op_sel_hi:[0,1]
	v_pk_fma_f32 v[100:101], v[174:175], v[100:101], v[110:111] neg_lo:[1,0,0] neg_hi:[1,0,0]
	s_nop 0
	v_pk_fma_f32 v[104:105], v[100:101], v[100:101], v[104:105]
	v_mul_f32_e32 v110, v101, v101
	v_pk_add_f32 v[104:105], v[104:105], v[110:111] op_sel_hi:[1,0]
	v_mul_f32_e32 v110, v97, v97
	v_pk_fma_f32 v[104:105], v[96:97], v[96:97], v[104:105]
	s_nop 0
	v_pk_add_f32 v[110:111], v[104:105], v[110:111] op_sel_hi:[1,0]
	s_waitcnt vmcnt(12)
	v_lshlrev_b32_e32 v104, 16, v109
	v_and_b32_e32 v105, 0xffff0000, v109
	v_pk_fma_f32 v[104:105], v[174:175], v[114:115], v[104:105] neg_lo:[1,0,0] neg_hi:[1,0,0]
	v_lshlrev_b32_e32 v114, 16, v108
	v_and_b32_e32 v115, 0xffff0000, v108
	v_pk_mul_f32 v[108:109], v[0:1], v[48:49] op_sel_hi:[0,1]
	v_pk_fma_f32 v[108:109], v[174:175], v[108:109], v[114:115] neg_lo:[1,0,0] neg_hi:[1,0,0]
	s_nop 0
	v_pk_fma_f32 v[110:111], v[108:109], v[108:109], v[110:111]
	v_mul_f32_e32 v114, v109, v109
	v_pk_add_f32 v[110:111], v[110:111], v[114:115] op_sel_hi:[1,0]
	v_mul_f32_e32 v114, v105, v105
	v_pk_fma_f32 v[110:111], v[104:105], v[104:105], v[110:111]
	s_nop 0
	v_pk_add_f32 v[114:115], v[110:111], v[114:115] op_sel_hi:[1,0]
	s_waitcnt vmcnt(11)
; __device__ __forceinline__ float bflo(unsigned w) { return __uint_as_float(w << 16); }
; __device__ __forceinline__ float bfhi(unsigned w) { return __uint_as_float(w & 0xffff0000u); }
; __global__ void __launch_bounds__(NWAVES * 64, 2) mega_fwd(Args args) {
;     ...
;                             for (int ig = 0; ig < 4; ++ig) { const v2u o1w = *(const v2u*)(srow + db * 32 + ig * 8 + 4 * hi); const f32x4 o1 = {bflo(o1w.x), bfhi(o1w.x), bflo(o1w.y), bfhi(o1w.y)};
; #pragma unroll
;                                 for (int e = 0; e < 4; ++e) { const float a = o1[e] - lam * (o[db][4 * ig + e] * inv); o[db][4 * ig + e] = a; ss += a * a; } }
	v_lshlrev_b32_e32 v110, 16, v113
	v_and_b32_e32 v111, 0xffff0000, v113
	v_pk_fma_f32 v[110:111], v[174:175], v[116:117], v[110:111] neg_lo:[1,0,0] neg_hi:[1,0,0]
	v_lshlrev_b32_e32 v116, 16, v112
	v_and_b32_e32 v117, 0xffff0000, v112
	v_pk_mul_f32 v[112:113], v[0:1], v[52:53] op_sel_hi:[0,1]
	v_pk_fma_f32 v[112:113], v[174:175], v[112:113], v[116:117] neg_lo:[1,0,0] neg_hi:[1,0,0]
	s_nop 0
	v_pk_fma_f32 v[114:115], v[112:113], v[112:113], v[114:115]
	v_mul_f32_e32 v116, v113, v113
	v_pk_add_f32 v[114:115], v[114:115], v[116:117] op_sel_hi:[1,0]
	v_mul_f32_e32 v116, v111, v111
	v_pk_fma_f32 v[114:115], v[110:111], v[110:111], v[114:115]
	s_nop 0
	v_pk_add_f32 v[116:117], v[114:115], v[116:117] op_sel_hi:[1,0]
	s_waitcnt vmcnt(10)
	v_lshlrev_b32_e32 v114, 16, v107
	v_and_b32_e32 v115, 0xffff0000, v107
	v_pk_fma_f32 v[114:115], v[174:175], v[118:119], v[114:115] neg_lo:[1,0,0] neg_hi:[1,0,0]
	v_lshlrev_b32_e32 v118, 16, v106
	v_and_b32_e32 v119, 0xffff0000, v106
	v_pk_mul_f32 v[106:107], v[0:1], v[56:57] op_sel_hi:[0,1]
	v_pk_fma_f32 v[134:135], v[174:175], v[106:107], v[118:119] neg_lo:[1,0,0] neg_hi:[1,0,0]
	v_pk_mul_f32 v[118:119], v[0:1], v[62:63] op_sel_hi:[0,1]
	v_pk_fma_f32 v[106:107], v[134:135], v[134:135], v[116:117]
	v_mul_f32_e32 v116, v135, v135
	v_pk_add_f32 v[106:107], v[106:107], v[116:117] op_sel_hi:[1,0]
	v_mul_f32_e32 v116, v115, v115
	v_pk_fma_f32 v[106:107], v[114:115], v[114:115], v[106:107]
	s_nop 0
	v_pk_add_f32 v[106:107], v[106:107], v[116:117] op_sel_hi:[1,0]
	s_waitcnt vmcnt(9)
	v_lshlrev_b32_e32 v116, 16, v103
	v_and_b32_e32 v117, 0xffff0000, v103
	v_pk_fma_f32 v[122:123], v[174:175], v[118:119], v[116:117] neg_lo:[1,0,0] neg_hi:[1,0,0]
	v_lshlrev_b32_e32 v116, 16, v102
	v_and_b32_e32 v117, 0xffff0000, v102
	v_pk_mul_f32 v[102:103], v[0:1], v[60:61] op_sel_hi:[0,1]
	v_pk_fma_f32 v[132:133], v[174:175], v[102:103], v[116:117] neg_lo:[1,0,0] neg_hi:[1,0,0]
	v_pk_mul_f32 v[116:117], v[0:1], v[34:35] op_sel_hi:[0,1]
	v_pk_fma_f32 v[102:103], v[132:133], v[132:133], v[106:107]
	v_mul_f32_e32 v106, v133, v133
	v_pk_add_f32 v[102:103], v[102:103], v[106:107] op_sel_hi:[1,0]
	v_mul_f32_e32 v106, v123, v123
	v_pk_fma_f32 v[102:103], v[122:123], v[122:123], v[102:103]
	s_nop 0
	v_pk_add_f32 v[102:103], v[102:103], v[106:107] op_sel_hi:[1,0]
	s_waitcnt vmcnt(8)
	v_lshlrev_b32_e32 v106, 16, v99
	v_and_b32_e32 v107, 0xffff0000, v99
	v_pk_fma_f32 v[118:119], v[174:175], v[116:117], v[106:107] neg_lo:[1,0,0] neg_hi:[1,0,0]
	v_lshlrev_b32_e32 v106, 16, v98
	v_and_b32_e32 v107, 0xffff0000, v98
	v_pk_mul_f32 v[98:99], v[0:1], v[32:33] op_sel_hi:[0,1]
	v_pk_fma_f32 v[130:131], v[174:175], v[98:99], v[106:107] neg_lo:[1,0,0] neg_hi:[1,0,0]
	v_pk_mul_f32 v[106:107], v[0:1], v[38:39] op_sel_hi:[0,1]
	v_pk_fma_f32 v[98:99], v[130:131], v[130:131], v[102:103]
	v_mul_f32_e32 v102, v131, v131
	v_pk_add_f32 v[98:99], v[98:99], v[102:103] op_sel_hi:[1,0]
	v_mul_f32_e32 v102, v119, v119
	v_pk_fma_f32 v[98:99], v[118:119], v[118:119], v[98:99]
	s_nop 0
	v_pk_add_f32 v[98:99], v[98:99], v[102:103] op_sel_hi:[1,0]
	s_waitcnt vmcnt(7)
	v_lshlrev_b32_e32 v102, 16, v95
	v_and_b32_e32 v103, 0xffff0000, v95
	v_pk_fma_f32 v[102:103], v[174:175], v[106:107], v[102:103] neg_lo:[1,0,0] neg_hi:[1,0,0]
	v_lshlrev_b32_e32 v106, 16, v94
	v_and_b32_e32 v107, 0xffff0000, v94
	v_pk_mul_f32 v[94:95], v[0:1], v[36:37] op_sel_hi:[0,1]
	v_pk_fma_f32 v[128:129], v[174:175], v[94:95], v[106:107] neg_lo:[1,0,0] neg_hi:[1,0,0]
	v_pk_mul_f32 v[106:107], v[0:1], v[42:43] op_sel_hi:[0,1]
	v_pk_fma_f32 v[94:95], v[128:129], v[128:129], v[98:99]
	v_mul_f32_e32 v98, v129, v129
	v_pk_add_f32 v[94:95], v[94:95], v[98:99] op_sel_hi:[1,0]
	v_mul_f32_e32 v98, v103, v103
	v_pk_fma_f32 v[94:95], v[102:103], v[102:103], v[94:95]
	s_nop 0
	v_pk_add_f32 v[98:99], v[94:95], v[98:99] op_sel_hi:[1,0]
	s_waitcnt vmcnt(6)
	v_lshlrev_b32_e32 v94, 16, v91
	v_and_b32_e32 v95, 0xffff0000, v91
	v_pk_fma_f32 v[94:95], v[174:175], v[106:107], v[94:95] neg_lo:[1,0,0] neg_hi:[1,0,0]
	v_lshlrev_b32_e32 v106, 16, v90
	v_and_b32_e32 v107, 0xffff0000, v90
	v_pk_mul_f32 v[90:91], v[0:1], v[40:41] op_sel_hi:[0,1]
	v_pk_fma_f32 v[126:127], v[174:175], v[90:91], v[106:107] neg_lo:[1,0,0] neg_hi:[1,0,0]
	v_pk_mul_f32 v[106:107], v[0:1], v[46:47] op_sel_hi:[0,1]
	v_pk_fma_f32 v[90:91], v[126:127], v[126:127], v[98:99]
	v_mul_f32_e32 v98, v127, v127
	v_pk_add_f32 v[90:91], v[90:91], v[98:99] op_sel_hi:[1,0]
	v_mul_f32_e32 v98, v95, v95
	v_pk_fma_f32 v[90:91], v[94:95], v[94:95], v[90:91]
	s_nop 0
	v_pk_add_f32 v[98:99], v[90:91], v[98:99] op_sel_hi:[1,0]
	s_waitcnt vmcnt(5)
	v_lshlrev_b32_e32 v90, 16, v87
	v_and_b32_e32 v91, 0xffff0000, v87
	v_pk_fma_f32 v[90:91], v[174:175], v[106:107], v[90:91] neg_lo:[1,0,0] neg_hi:[1,0,0]
	v_lshlrev_b32_e32 v106, 16, v86
	v_and_b32_e32 v107, 0xffff0000, v86
	v_pk_mul_f32 v[86:87], v[0:1], v[44:45] op_sel_hi:[0,1]
	v_pk_fma_f32 v[124:125], v[174:175], v[86:87], v[106:107] neg_lo:[1,0,0] neg_hi:[1,0,0]
	v_pk_mul_f32 v[106:107], v[0:1], v[18:19] op_sel_hi:[0,1]
	v_pk_fma_f32 v[86:87], v[124:125], v[124:125], v[98:99]
	v_mul_f32_e32 v98, v125, v125
	v_pk_add_f32 v[86:87], v[86:87], v[98:99] op_sel_hi:[1,0]
	v_mul_f32_e32 v98, v91, v91
	v_pk_fma_f32 v[86:87], v[90:91], v[90:91], v[86:87]
	s_nop 0
	v_pk_add_f32 v[98:99], v[86:87], v[98:99] op_sel_hi:[1,0]
	s_waitcnt vmcnt(4)
; __device__ __forceinline__ float bflo(unsigned w) { return __uint_as_float(w << 16); }
; __device__ __forceinline__ float bfhi(unsigned w) { return __uint_as_float(w & 0xffff0000u); }
; __device__ __forceinline__ float half_sum(float v) { float a, b; half_pair(v, a, b); return a + b; }
; __global__ void __launch_bounds__(NWAVES * 64, 2) mega_fwd(Args args) {
;     ...
;                             for (int ig = 0; ig < 4; ++ig) { const v2u o1w = *(const v2u*)(srow + db * 32 + ig * 8 + 4 * hi); const f32x4 o1 = {bflo(o1w.x), bfhi(o1w.x), bflo(o1w.y), bfhi(o1w.y)};
; #pragma unroll
;                                 for (int e = 0; e < 4; ++e) { const float a = o1[e] - lam * (o[db][4 * ig + e] * inv); o[db][4 * ig + e] = a; ss += a * a; } }
;                         ss = half_sum(ss);
;                         const float rstd = rsqrtf(ss * (1.f / 128.f) + EPS) * 0.8f;
;                         bf16* orow = O + (size_t)(tokb + qw + r32) * AB_OUT + h * 128;
; #pragma unroll
;                         for (int db = 0; db < 4; ++db)
; #pragma unroll
;                             for (int ig = 0; ig < 4; ++ig) { const f32x4 gn = *(const f32x4*)(ap->in[8] + db * 32 + ig * 8 + 4 * hi); v2u w;
;                                 w.x = cvtpk(o[db][4 * ig] * rstd * gn.x, o[db][4 * ig + 1] * rstd * gn.y); w.y = cvtpk(o[db][4 * ig + 2] * rstd * gn.z, o[db][4 * ig + 3] * rstd * gn.w);
;                                 *(v2u*)(orow + db * 32 + ig * 8 + 4 * hi) = w; }
	v_lshlrev_b32_e32 v86, 16, v85
	v_and_b32_e32 v87, 0xffff0000, v85
	v_pk_fma_f32 v[86:87], v[174:175], v[106:107], v[86:87] neg_lo:[1,0,0] neg_hi:[1,0,0]
	v_lshlrev_b32_e32 v106, 16, v84
	v_and_b32_e32 v107, 0xffff0000, v84
	v_pk_mul_f32 v[84:85], v[0:1], v[16:17] op_sel_hi:[0,1]
	v_pk_fma_f32 v[116:117], v[174:175], v[84:85], v[106:107] neg_lo:[1,0,0] neg_hi:[1,0,0]
	v_pk_mul_f32 v[106:107], v[0:1], v[22:23] op_sel_hi:[0,1]
	v_pk_fma_f32 v[84:85], v[116:117], v[116:117], v[98:99]
	v_mul_f32_e32 v98, v117, v117
	v_pk_add_f32 v[84:85], v[84:85], v[98:99] op_sel_hi:[1,0]
	v_mul_f32_e32 v98, v87, v87
	v_pk_fma_f32 v[84:85], v[86:87], v[86:87], v[84:85]
	s_nop 0
	v_pk_add_f32 v[98:99], v[84:85], v[98:99] op_sel_hi:[1,0]
	s_waitcnt vmcnt(3)
	v_lshlrev_b32_e32 v84, 16, v81
	v_and_b32_e32 v85, 0xffff0000, v81
	v_pk_fma_f32 v[84:85], v[174:175], v[106:107], v[84:85] neg_lo:[1,0,0] neg_hi:[1,0,0]
	v_lshlrev_b32_e32 v106, 16, v80
	v_and_b32_e32 v107, 0xffff0000, v80
	v_pk_mul_f32 v[80:81], v[0:1], v[20:21] op_sel_hi:[0,1]
	v_pk_fma_f32 v[106:107], v[174:175], v[80:81], v[106:107] neg_lo:[1,0,0] neg_hi:[1,0,0]
	s_nop 0
	v_pk_fma_f32 v[80:81], v[106:107], v[106:107], v[98:99]
	v_mul_f32_e32 v98, v107, v107
	v_pk_add_f32 v[80:81], v[80:81], v[98:99] op_sel_hi:[1,0]
	v_mul_f32_e32 v98, v85, v85
	v_pk_fma_f32 v[80:81], v[84:85], v[84:85], v[80:81]
	s_nop 0
	v_pk_add_f32 v[136:137], v[80:81], v[98:99] op_sel_hi:[1,0]
	s_waitcnt vmcnt(2)
	v_lshlrev_b32_e32 v80, 16, v13
	v_and_b32_e32 v81, 0xffff0000, v13
	v_pk_mul_f32 v[98:99], v[0:1], v[26:27] op_sel_hi:[0,1]
	v_pk_fma_f32 v[80:81], v[174:175], v[98:99], v[80:81] neg_lo:[1,0,0] neg_hi:[1,0,0]
	v_lshlrev_b32_e32 v98, 16, v12
	v_and_b32_e32 v99, 0xffff0000, v12
	v_pk_mul_f32 v[12:13], v[0:1], v[24:25] op_sel_hi:[0,1]
	v_pk_fma_f32 v[98:99], v[174:175], v[12:13], v[98:99] neg_lo:[1,0,0] neg_hi:[1,0,0]
	s_nop 0
	v_pk_fma_f32 v[12:13], v[98:99], v[98:99], v[136:137]
	v_mul_f32_e32 v120, v99, v99
	v_pk_add_f32 v[12:13], v[12:13], v[120:121] op_sel_hi:[1,0]
	v_mul_f32_e32 v120, v81, v81
	v_pk_fma_f32 v[12:13], v[80:81], v[80:81], v[12:13]
	s_nop 0
	v_pk_add_f32 v[136:137], v[12:13], v[120:121] op_sel_hi:[1,0]
	s_waitcnt vmcnt(1)
	v_lshlrev_b32_e32 v12, 16, v9
	v_and_b32_e32 v13, 0xffff0000, v9
	v_pk_fma_f32 v[12:13], v[174:175], v[138:139], v[12:13] neg_lo:[1,0,0] neg_hi:[1,0,0]
	v_lshlrev_b32_e32 v138, 16, v8
	v_and_b32_e32 v139, 0xffff0000, v8
	v_pk_mul_f32 v[8:9], v[0:1], v[28:29] op_sel_hi:[0,1]
	v_pk_fma_f32 v[8:9], v[174:175], v[8:9], v[138:139] neg_lo:[1,0,0] neg_hi:[1,0,0]
	s_nop 0
	v_pk_fma_f32 v[136:137], v[8:9], v[8:9], v[136:137]
	v_mul_f32_e32 v120, v9, v9
	v_pk_add_f32 v[136:137], v[136:137], v[120:121] op_sel_hi:[1,0]
	v_mul_f32_e32 v120, v13, v13
	v_pk_fma_f32 v[136:137], v[12:13], v[12:13], v[136:137]
	s_nop 0
	v_pk_add_f32 v[136:137], v[136:137], v[120:121] op_sel_hi:[1,0]
	s_nop 0
	v_mov_b32_e32 v120, v136
	s_nop 1
	v_permlane32_swap_b32_e32 v136, v120
	v_add_f32_e32 v120, v136, v120
	v_fmamk_f32 v120, v120, 0x3c000000, v236
	v_cmp_gt_f32_e32 vcc, s40, v120
	v_mul_f32_e32 v136, 0x4b800000, v120
	s_nop 0
	v_cndmask_b32_e32 v120, v120, v136, vcc
	v_rsq_f32_e32 v120, v120
	s_nop 0
	v_mul_f32_e32 v136, 0x45800000, v120
	v_cndmask_b32_e32 v120, v120, v136, vcc
	v_mul_f32_e32 v120, 0x3f4ccccd, v120
	v_pk_mul_f32 v[10:11], v[120:121], v[10:11] op_sel_hi:[0,1]
	v_pk_mul_f32 v[6:7], v[120:121], v[6:7] op_sel_hi:[0,1]
	global_load_dwordx4 v[144:147], v121, s[92:93] offset:32
	global_load_dwordx4 v[148:151], v121, s[92:93] offset:64
	global_load_dwordx4 v[152:155], v121, s[92:93] offset:96
	global_load_dwordx4 v[156:159], v121, s[92:93] offset:128
	global_load_dwordx4 v[160:163], v121, s[92:93] offset:160
	global_load_dwordx4 v[164:167], v121, s[92:93] offset:192
	global_load_dwordx4 v[168:171], v121, s[92:93] offset:224
	s_waitcnt vmcnt(7)
	v_pk_mul_f32 v[2:3], v[2:3], v[10:11]
	v_pk_mul_f32 v[4:5], v[4:5], v[6:7]
	v_cvt_pk_bf16_f32 v2, v2, v3
	v_cvt_pk_bf16_f32 v3, v4, v5
	global_store_dwordx2 v[234:235], v[2:3], off
	global_load_dwordx4 v[140:143], v121, s[92:93] offset:256
	v_pk_mul_f32 v[6:7], v[120:121], v[82:83] op_sel_hi:[0,1]
	s_waitcnt vmcnt(8)
	v_pk_mul_f32 v[2:3], v[144:145], v[6:7]
	v_pk_mul_f32 v[6:7], v[120:121], v[14:15] op_sel_hi:[0,1]
	v_pk_mul_f32 v[4:5], v[146:147], v[6:7]
	v_cvt_pk_bf16_f32 v2, v2, v3
	v_cvt_pk_bf16_f32 v3, v4, v5
	global_store_dwordx2 v[234:235], v[2:3], off offset:16
	global_load_dwordx4 v[144:147], v121, s[92:93] offset:288
	v_pk_mul_f32 v[6:7], v[120:121], v[92:93] op_sel_hi:[0,1]
	s_waitcnt vmcnt(9)
	v_pk_mul_f32 v[2:3], v[148:149], v[6:7]
	v_pk_mul_f32 v[6:7], v[120:121], v[88:89] op_sel_hi:[0,1]
	v_pk_mul_f32 v[4:5], v[150:151], v[6:7]
	v_cvt_pk_bf16_f32 v2, v2, v3
	v_cvt_pk_bf16_f32 v3, v4, v5
	global_store_dwordx2 v[234:235], v[2:3], off offset:32
	global_load_dwordx4 v[148:151], v121, s[92:93] offset:320
	v_pk_mul_f32 v[6:7], v[120:121], v[100:101] op_sel_hi:[0,1]
	s_waitcnt vmcnt(10)
; __global__ void __launch_bounds__(NWAVES * 64, 2) mega_fwd(Args args) {
;     ...
; #pragma unroll
;                         for (int db = 0; db < 4; ++db)
; #pragma unroll
;                             for (int ig = 0; ig < 4; ++ig) { const f32x4 gn = *(const f32x4*)(ap->in[8] + db * 32 + ig * 8 + 4 * hi); v2u w;
;                                 w.x = cvtpk(o[db][4 * ig] * rstd * gn.x, o[db][4 * ig + 1] * rstd * gn.y); w.y = cvtpk(o[db][4 * ig + 2] * rstd * gn.z, o[db][4 * ig + 3] * rstd * gn.w);
;                                 *(v2u*)(orow + db * 32 + ig * 8 + 4 * hi) = w; }
	v_pk_mul_f32 v[2:3], v[152:153], v[6:7]
	v_pk_mul_f32 v[6:7], v[120:121], v[96:97] op_sel_hi:[0,1]
	v_pk_mul_f32 v[4:5], v[154:155], v[6:7]
	v_cvt_pk_bf16_f32 v2, v2, v3
	v_cvt_pk_bf16_f32 v3, v4, v5
	global_store_dwordx2 v[234:235], v[2:3], off offset:48
	global_load_dwordx4 v[152:155], v121, s[92:93] offset:352
	v_pk_mul_f32 v[6:7], v[120:121], v[108:109] op_sel_hi:[0,1]
	s_waitcnt vmcnt(11)
	v_pk_mul_f32 v[2:3], v[156:157], v[6:7]
	v_pk_mul_f32 v[6:7], v[120:121], v[104:105] op_sel_hi:[0,1]
	v_pk_mul_f32 v[4:5], v[158:159], v[6:7]
	v_cvt_pk_bf16_f32 v2, v2, v3
	v_cvt_pk_bf16_f32 v3, v4, v5
	global_store_dwordx2 v[234:235], v[2:3], off offset:64
	global_load_dwordx4 v[156:159], v121, s[92:93] offset:384
	v_pk_mul_f32 v[6:7], v[120:121], v[112:113] op_sel_hi:[0,1]
	s_waitcnt vmcnt(12)
	v_pk_mul_f32 v[2:3], v[160:161], v[6:7]
	v_pk_mul_f32 v[6:7], v[120:121], v[110:111] op_sel_hi:[0,1]
	v_pk_mul_f32 v[4:5], v[162:163], v[6:7]
	v_cvt_pk_bf16_f32 v2, v2, v3
	v_cvt_pk_bf16_f32 v3, v4, v5
	global_store_dwordx2 v[234:235], v[2:3], off offset:80
	global_load_dwordx4 v[160:163], v121, s[92:93] offset:416
	v_pk_mul_f32 v[6:7], v[120:121], v[134:135] op_sel_hi:[0,1]
	s_waitcnt vmcnt(13)
	v_pk_mul_f32 v[2:3], v[164:165], v[6:7]
	v_pk_mul_f32 v[6:7], v[120:121], v[114:115] op_sel_hi:[0,1]
	v_pk_mul_f32 v[4:5], v[166:167], v[6:7]
	v_cvt_pk_bf16_f32 v2, v2, v3
	v_cvt_pk_bf16_f32 v3, v4, v5
	global_store_dwordx2 v[234:235], v[2:3], off offset:96
	global_load_dwordx4 v[164:167], v121, s[92:93] offset:448
	v_pk_mul_f32 v[6:7], v[120:121], v[132:133] op_sel_hi:[0,1]
	s_waitcnt vmcnt(14)
	v_pk_mul_f32 v[2:3], v[168:169], v[6:7]
	v_pk_mul_f32 v[6:7], v[120:121], v[122:123] op_sel_hi:[0,1]
	v_pk_mul_f32 v[4:5], v[170:171], v[6:7]
	v_cvt_pk_bf16_f32 v2, v2, v3
	v_cvt_pk_bf16_f32 v3, v4, v5
	global_store_dwordx2 v[234:235], v[2:3], off offset:112
	global_load_dwordx4 v[168:171], v121, s[92:93] offset:480
	v_pk_mul_f32 v[6:7], v[120:121], v[130:131] op_sel_hi:[0,1]
	s_waitcnt vmcnt(14)
	v_pk_mul_f32 v[2:3], v[140:141], v[6:7]
	v_pk_mul_f32 v[6:7], v[120:121], v[118:119] op_sel_hi:[0,1]
	v_pk_mul_f32 v[4:5], v[142:143], v[6:7]
	v_cvt_pk_bf16_f32 v2, v2, v3
	v_cvt_pk_bf16_f32 v3, v4, v5
	global_store_dwordx2 v[234:235], v[2:3], off offset:128
	v_pk_mul_f32 v[6:7], v[120:121], v[128:129] op_sel_hi:[0,1]
	s_waitcnt vmcnt(13)
	v_pk_mul_f32 v[2:3], v[144:145], v[6:7]
	v_pk_mul_f32 v[6:7], v[120:121], v[102:103] op_sel_hi:[0,1]
	v_pk_mul_f32 v[4:5], v[146:147], v[6:7]
	v_cvt_pk_bf16_f32 v2, v2, v3
	v_cvt_pk_bf16_f32 v3, v4, v5
	global_store_dwordx2 v[234:235], v[2:3], off offset:144
	v_pk_mul_f32 v[6:7], v[120:121], v[126:127] op_sel_hi:[0,1]
	s_waitcnt vmcnt(12)
	v_pk_mul_f32 v[2:3], v[148:149], v[6:7]
	v_pk_mul_f32 v[6:7], v[120:121], v[94:95] op_sel_hi:[0,1]
	v_pk_mul_f32 v[4:5], v[150:151], v[6:7]
	v_cvt_pk_bf16_f32 v2, v2, v3
	v_cvt_pk_bf16_f32 v3, v4, v5
	global_store_dwordx2 v[234:235], v[2:3], off offset:160
	v_pk_mul_f32 v[6:7], v[120:121], v[124:125] op_sel_hi:[0,1]
	s_waitcnt vmcnt(11)
	v_pk_mul_f32 v[2:3], v[152:153], v[6:7]
	v_pk_mul_f32 v[6:7], v[120:121], v[90:91] op_sel_hi:[0,1]
	v_pk_mul_f32 v[4:5], v[154:155], v[6:7]
	v_cvt_pk_bf16_f32 v2, v2, v3
	v_cvt_pk_bf16_f32 v3, v4, v5
	global_store_dwordx2 v[234:235], v[2:3], off offset:176
	v_pk_mul_f32 v[6:7], v[120:121], v[116:117] op_sel_hi:[0,1]
	s_waitcnt vmcnt(10)
	v_pk_mul_f32 v[2:3], v[156:157], v[6:7]
	v_pk_mul_f32 v[6:7], v[120:121], v[86:87] op_sel_hi:[0,1]
	v_pk_mul_f32 v[4:5], v[158:159], v[6:7]
	v_cvt_pk_bf16_f32 v2, v2, v3
	v_cvt_pk_bf16_f32 v3, v4, v5
	global_store_dwordx2 v[234:235], v[2:3], off offset:192
	v_pk_mul_f32 v[6:7], v[120:121], v[106:107] op_sel_hi:[0,1]
	s_waitcnt vmcnt(9)
	v_pk_mul_f32 v[2:3], v[160:161], v[6:7]
	v_pk_mul_f32 v[6:7], v[120:121], v[84:85] op_sel_hi:[0,1]
	v_pk_mul_f32 v[4:5], v[162:163], v[6:7]
	v_cvt_pk_bf16_f32 v2, v2, v3
	v_cvt_pk_bf16_f32 v3, v4, v5
	global_store_dwordx2 v[234:235], v[2:3], off offset:208
	v_pk_mul_f32 v[6:7], v[120:121], v[98:99] op_sel_hi:[0,1]
	s_waitcnt vmcnt(8)
	v_pk_mul_f32 v[2:3], v[164:165], v[6:7]
	v_pk_mul_f32 v[6:7], v[120:121], v[80:81] op_sel_hi:[0,1]
	v_pk_mul_f32 v[4:5], v[166:167], v[6:7]
	v_cvt_pk_bf16_f32 v2, v2, v3
	v_cvt_pk_bf16_f32 v3, v4, v5
	global_store_dwordx2 v[234:235], v[2:3], off offset:224
	v_pk_mul_f32 v[6:7], v[120:121], v[8:9] op_sel_hi:[0,1]
	s_waitcnt vmcnt(7)
	v_pk_mul_f32 v[2:3], v[168:169], v[6:7]
	v_pk_mul_f32 v[6:7], v[120:121], v[12:13] op_sel_hi:[0,1]
	v_pk_mul_f32 v[4:5], v[170:171], v[6:7]
	v_cvt_pk_bf16_f32 v2, v2, v3
	v_cvt_pk_bf16_f32 v3, v4, v5
	global_store_dwordx2 v[234:235], v[2:3], off offset:240
	s_cbranch_execnz .LBB0_264
	s_branch .LBB0_288

; __device__ __forceinline__ float bflo(unsigned w) { return __uint_as_float(w << 16); }
; __device__ __forceinline__ float bfhi(unsigned w) { return __uint_as_float(w & 0xffff0000u); }
; __global__ void __launch_bounds__(NWAVES * 64, 2) mega_fwd(Args args) {
;     ...
;                 for (int j = gw; j < NB * 8 * 16; j += ngw) {
;                 const int blk = j & 15, h = (j >> 4) & 7, b = j >> 7;
;                 const bf16* kp = Z + (size_t)(b * SEQ + blk * 256) * CD_INP + 1856 + h * 128 + 2 * lane; float s0 = 0.f, s1 = 0.f;
; #pragma unroll 16
;                 for (int t = 0; t < 256; ++t) { const unsigned w = *(const unsigned*)(kp + (size_t)t * CD_INP); s0 += bflo(w); s1 += bfhi(w); }
.LBB0_391:
	s_cmpk_gt_i32 s76, 0x1ff
	s_cbranch_scc1 .LBB0_396
	v_lshlrev_b32_e32 v0, 3, v244
	v_lshl_add_u64 v[2:3], s[72:73], 0, v[0:1]
	s_mov_b64 s[6:7], 0x400000
	v_lshl_add_u64 v[2:3], v[2:3], 0, s[6:7]
	s_lshl_b32 s3, s2, 8
	s_lshl_b32 s6, s93, 5
	s_add_i32 s3, s3, s6
	s_lshl_b32 s6, s2, 11
	s_lshl_b32 s7, s93, 8
	v_lshlrev_b32_e32 v0, 2, v244
	s_add_i32 s11, s6, s7
	s_lshl_b32 s6, s2, 6
	s_lshl_b32 s7, s93, 3
	v_lshl_add_u64 v[4:5], s[72:73], 0, v[0:1]
	v_add_u32_e32 v16, 0x0, v0
	v_add_u32_e32 v17, 0x2080, v0
	v_add_u32_e32 v18, 0x4100, v0
	v_add_u32_e32 v19, 0x6180, v0
	v_add_u32_e32 v20, 0x8200, v0
	v_add_u32_e32 v21, 0xa280, v0
	v_add_u32_e32 v22, 0xc300, v0
	v_add_u32_e32 v23, 0xe380, v0
	v_add_u32_e32 v24, 0x10400, v0
	v_add_u32_e32 v25, 0x12480, v0
	v_add_u32_e32 v26, 0x14500, v0
	v_add_u32_e32 v27, 0x16580, v0
	v_add_u32_e32 v28, 0x18600, v0
	v_add_u32_e32 v29, 0x1a680, v0
	v_add_u32_e32 v30, 0x1c700, v0
	v_add_u32_e32 v31, 0x1e780, v0
	s_lshl_b32 s10, s48, 8
	s_lshl_b32 s12, s48, 11
	s_add_i32 s13, s6, s7
	s_lshl_b32 s14, s48, 6
	s_mov_b32 s6, s76
.LBB0_393:
	s_and_b32 s7, s3, 0xfffff000
	s_and_b32 s8, s11, 0xf00
	s_or_b32 s7, s7, s8
	s_lshl_b32 s8, s13, 1
	s_mul_hi_i32 s9, s7, 0x2080
	s_mulk_i32 s7, 0x2080
	s_and_b32 s8, s8, 0x700
	s_or_b32 s8, s7, s8
	v_mov_b32_e32 v10, 0
	s_add_u32 s8, s8, s72
	s_addc_u32 s9, s9, s73
	s_add_u32 s8, s8, 0x26200e80
	s_addc_u32 s9, s9, 0
	s_movk_i32 s7, 8
	v_mov_b32_e32 v11, v10
	global_load_dword v32, v16, s[8:9]
	global_load_dword v33, v17, s[8:9]
	global_load_dword v34, v18, s[8:9]
	global_load_dword v35, v19, s[8:9]
	global_load_dword v36, v20, s[8:9]
	global_load_dword v37, v21, s[8:9]
	global_load_dword v38, v22, s[8:9]
	global_load_dword v39, v23, s[8:9]
	global_load_dword v40, v24, s[8:9]
	global_load_dword v41, v25, s[8:9]
	global_load_dword v42, v26, s[8:9]
	global_load_dword v43, v27, s[8:9]
	global_load_dword v44, v28, s[8:9]
	global_load_dword v45, v29, s[8:9]
	global_load_dword v46, v30, s[8:9]
	global_load_dword v47, v31, s[8:9]
	s_add_u32 s8, s8, 0x20800
	s_addc_u32 s9, s9, 0
; __device__ __forceinline__ float bflo(unsigned w) { return __uint_as_float(w << 16); }
; __device__ __forceinline__ float bfhi(unsigned w) { return __uint_as_float(w & 0xffff0000u); }
; __global__ void __launch_bounds__(NWAVES * 64, 2) mega_fwd(Args args) {
;     ...
; #pragma unroll 16
;                 for (int t = 0; t < 256; ++t) { const unsigned w = *(const unsigned*)(kp + (size_t)t * CD_INP); s0 += bflo(w); s1 += bfhi(w); }
;                 KMEAN[(size_t)j * 128 + 2 * lane] = s0 * (1.f / 256.f); KMEAN[(size_t)j * 128 + 2 * lane + 1] = s1 * (1.f / 256.f);
.Lkm_loop:
	global_load_dword v48, v16, s[8:9]
	global_load_dword v49, v17, s[8:9]
	global_load_dword v50, v18, s[8:9]
	global_load_dword v51, v19, s[8:9]
	global_load_dword v52, v20, s[8:9]
	global_load_dword v53, v21, s[8:9]
	global_load_dword v54, v22, s[8:9]
	global_load_dword v55, v23, s[8:9]
	global_load_dword v56, v24, s[8:9]
	global_load_dword v57, v25, s[8:9]
	global_load_dword v58, v26, s[8:9]
	global_load_dword v59, v27, s[8:9]
	global_load_dword v60, v28, s[8:9]
	global_load_dword v61, v29, s[8:9]
	global_load_dword v62, v30, s[8:9]
	global_load_dword v63, v31, s[8:9]
	s_add_u32 s8, s8, 0x20800
	s_addc_u32 s9, s9, 0
	s_waitcnt vmcnt(16)
	v_lshlrev_b32_e32 v12, 16, v32
	v_and_b32_e32 v13, 0xffff0000, v32
	v_pk_add_f32 v[10:11], v[10:11], v[12:13]
	v_lshlrev_b32_e32 v12, 16, v33
	v_and_b32_e32 v13, 0xffff0000, v33
	v_pk_add_f32 v[10:11], v[10:11], v[12:13]
	v_lshlrev_b32_e32 v12, 16, v34
	v_and_b32_e32 v13, 0xffff0000, v34
	v_pk_add_f32 v[10:11], v[10:11], v[12:13]
	v_lshlrev_b32_e32 v12, 16, v35
	v_and_b32_e32 v13, 0xffff0000, v35
	v_pk_add_f32 v[10:11], v[10:11], v[12:13]
	v_lshlrev_b32_e32 v12, 16, v36
	v_and_b32_e32 v13, 0xffff0000, v36
	v_pk_add_f32 v[10:11], v[10:11], v[12:13]
	v_lshlrev_b32_e32 v12, 16, v37
	v_and_b32_e32 v13, 0xffff0000, v37
	v_pk_add_f32 v[10:11], v[10:11], v[12:13]
	v_lshlrev_b32_e32 v12, 16, v38
	v_and_b32_e32 v13, 0xffff0000, v38
	v_pk_add_f32 v[10:11], v[10:11], v[12:13]
	v_lshlrev_b32_e32 v12, 16, v39
	v_and_b32_e32 v13, 0xffff0000, v39
	v_pk_add_f32 v[10:11], v[10:11], v[12:13]
	v_lshlrev_b32_e32 v12, 16, v40
	v_and_b32_e32 v13, 0xffff0000, v40
	v_pk_add_f32 v[10:11], v[10:11], v[12:13]
	v_lshlrev_b32_e32 v12, 16, v41
	v_and_b32_e32 v13, 0xffff0000, v41
	v_pk_add_f32 v[10:11], v[10:11], v[12:13]
	v_lshlrev_b32_e32 v12, 16, v42
	v_and_b32_e32 v13, 0xffff0000, v42
	v_pk_add_f32 v[10:11], v[10:11], v[12:13]
	v_lshlrev_b32_e32 v12, 16, v43
	v_and_b32_e32 v13, 0xffff0000, v43
	v_pk_add_f32 v[10:11], v[10:11], v[12:13]
	v_lshlrev_b32_e32 v12, 16, v44
	v_and_b32_e32 v13, 0xffff0000, v44
	v_pk_add_f32 v[10:11], v[10:11], v[12:13]
	v_lshlrev_b32_e32 v12, 16, v45
	v_and_b32_e32 v13, 0xffff0000, v45
	v_pk_add_f32 v[10:11], v[10:11], v[12:13]
	v_lshlrev_b32_e32 v12, 16, v46
	v_and_b32_e32 v13, 0xffff0000, v46
	v_pk_add_f32 v[10:11], v[10:11], v[12:13]
	v_lshlrev_b32_e32 v12, 16, v47
	v_and_b32_e32 v13, 0xffff0000, v47
	v_pk_add_f32 v[10:11], v[10:11], v[12:13]
	global_load_dword v32, v16, s[8:9]
	global_load_dword v33, v17, s[8:9]
	global_load_dword v34, v18, s[8:9]
	global_load_dword v35, v19, s[8:9]
	global_load_dword v36, v20, s[8:9]
	global_load_dword v37, v21, s[8:9]
	global_load_dword v38, v22, s[8:9]
	global_load_dword v39, v23, s[8:9]
	global_load_dword v40, v24, s[8:9]
	global_load_dword v41, v25, s[8:9]
	global_load_dword v42, v26, s[8:9]
	global_load_dword v43, v27, s[8:9]
	global_load_dword v44, v28, s[8:9]
	global_load_dword v45, v29, s[8:9]
	global_load_dword v46, v30, s[8:9]
	global_load_dword v47, v31, s[8:9]
	s_add_u32 s8, s8, 0x20800
	s_addc_u32 s9, s9, 0
	s_waitcnt vmcnt(16)
	v_lshlrev_b32_e32 v12, 16, v48
	v_and_b32_e32 v13, 0xffff0000, v48
	v_pk_add_f32 v[10:11], v[10:11], v[12:13]
	v_lshlrev_b32_e32 v12, 16, v49
	v_and_b32_e32 v13, 0xffff0000, v49
	v_pk_add_f32 v[10:11], v[10:11], v[12:13]
	v_lshlrev_b32_e32 v12, 16, v50
	v_and_b32_e32 v13, 0xffff0000, v50
	v_pk_add_f32 v[10:11], v[10:11], v[12:13]
	v_lshlrev_b32_e32 v12, 16, v51
	v_and_b32_e32 v13, 0xffff0000, v51
	v_pk_add_f32 v[10:11], v[10:11], v[12:13]
	v_lshlrev_b32_e32 v12, 16, v52
	v_and_b32_e32 v13, 0xffff0000, v52
	v_pk_add_f32 v[10:11], v[10:11], v[12:13]
	v_lshlrev_b32_e32 v12, 16, v53
	v_and_b32_e32 v13, 0xffff0000, v53
	v_pk_add_f32 v[10:11], v[10:11], v[12:13]
	v_lshlrev_b32_e32 v12, 16, v54
	v_and_b32_e32 v13, 0xffff0000, v54
	v_pk_add_f32 v[10:11], v[10:11], v[12:13]
	v_lshlrev_b32_e32 v12, 16, v55
	v_and_b32_e32 v13, 0xffff0000, v55
	v_pk_add_f32 v[10:11], v[10:11], v[12:13]
	v_lshlrev_b32_e32 v12, 16, v56
	v_and_b32_e32 v13, 0xffff0000, v56
	v_pk_add_f32 v[10:11], v[10:11], v[12:13]
	v_lshlrev_b32_e32 v12, 16, v57
	v_and_b32_e32 v13, 0xffff0000, v57
	v_pk_add_f32 v[10:11], v[10:11], v[12:13]
	v_lshlrev_b32_e32 v12, 16, v58
	v_and_b32_e32 v13, 0xffff0000, v58
	v_pk_add_f32 v[10:11], v[10:11], v[12:13]
	v_lshlrev_b32_e32 v12, 16, v59
	v_and_b32_e32 v13, 0xffff0000, v59
	v_pk_add_f32 v[10:11], v[10:11], v[12:13]
	v_lshlrev_b32_e32 v12, 16, v60
	v_and_b32_e32 v13, 0xffff0000, v60
	v_pk_add_f32 v[10:11], v[10:11], v[12:13]
	v_lshlrev_b32_e32 v12, 16, v61
	v_and_b32_e32 v13, 0xffff0000, v61
	v_pk_add_f32 v[10:11], v[10:11], v[12:13]
	v_lshlrev_b32_e32 v12, 16, v62
	v_and_b32_e32 v13, 0xffff0000, v62
	v_pk_add_f32 v[10:11], v[10:11], v[12:13]
	v_lshlrev_b32_e32 v12, 16, v63
	v_and_b32_e32 v13, 0xffff0000, v63
	v_pk_add_f32 v[10:11], v[10:11], v[12:13]
	s_sub_i32 s7, s7, 1
	s_cmp_lg_u32 s7, 0
	s_cbranch_scc1 .Lkm_loop
	s_waitcnt vmcnt(0)
	s_mov_b32 s8, 0x3b800000
	s_ashr_i32 s7, s6, 31
	v_pk_mul_f32 v[6:7], v[10:11], s[8:9] op_sel_hi:[1,0]
	s_lshl_b64 s[8:9], s[6:7], 9
	s_add_i32 s6, s6, s78
	s_add_i32 s3, s3, s10
	s_add_i32 s11, s11, s12
	s_add_i32 s13, s13, s14
	v_lshl_add_u64 v[8:9], v[2:3], 0, s[8:9]
	s_cmpk_gt_i32 s6, 0x1ff
	global_store_dwordx2 v[8:9], v[6:7], off
	s_cbranch_scc0 .LBB0_393
